# store-ack decoupling: skinny residual units no longer wait for the first row's stores before the second row; final RMSNorm loop waits vmcnt(12) past the previous row's stores (first row peeled)
# speedup vs baseline: 1.0079x; 1.0064x over previous
; __device__ __forceinline__ unsigned pk2(float lo, float hi) { f32x2_t v = {lo, hi}; bf16x2_t b = __builtin_convertvector(v, bf16x2_t); return __builtin_bit_cast(unsigned, b); }
; __device__ __forceinline__ float bf1(bf16 b) { return __uint_as_float((unsigned)b << 16); }
; __device__ __forceinline__ float wave_sum(float v) { v = sum16(v); v += lane_xor<16>(v); return xhalf_sum(v); }
; template <bool FIRST> __device__ __forceinline__ void skinny_resid(const bf16* __restrict__ A, const bf16* __restrict__ Bt, int K, const float* xs, bf16* XB, float* SS, int u, LAS unsigned char* lds, int tid) {
;     ...
;     for (int rr = 0; rr < 2; ++rr) { const int lr = 2 * w + rr;
;         const int ct = lane >> 4, src_lane = (lr >> 2) * 16 + (lane & 15), reg = lr & 3;
;         float s = 0.f;
; #pragma unroll
;         for (int ww = 0; ww < 8; ++ww) s += red[((ww * 4 + ct) * 64 + src_lane) * 4 + reg];
;         const int srow = 16 * rt + lr; const size_t row = (size_t)NP + srow; const int col = 64 * cu + lane;
;         const float x = (FIRST ? xs[(size_t)srow * D + col] : bf1(XB[row * D + col])) + s;
;         XB[row * D + col] = (bf16)(pk2(x, 0.f) & 0xffffu);
;         const float sq = wave_sum(x * x);
;         if (lane == 0) SS[row * 16 + cu] = sq; }
.LBB0_717:
	s_or_b64 exec, exec, s[6:7]
	s_or_b32 s36, s36, 1
	s_add_i32 s4, s36, s35
	s_ashr_i32 s5, s4, 31
	s_lshl_b64 s[6:7], s[4:5], 11
	v_lshl_add_u64 v[2:3], v[2:3], 0, s[6:7]
	v_mov_b32_e32 v14, v242
	s_and_b32 s6, s36, 3
	s_lshl_b32 s6, s6, 2
	s_add_i32 s6, s6, 0
	v_add3_u32 v0, s6, v0, v6
	ds_read2st64_b32 v[6:7], v0 offset1:16
	ds_read2st64_b32 v[8:9], v0 offset0:32 offset1:48
	ds_read2st64_b32 v[10:11], v0 offset0:64 offset1:80
	ds_read2st64_b32 v[12:13], v0 offset0:96 offset1:112
	s_waitcnt lgkmcnt(3)
	v_add_f32_e32 v0, 0, v6
	v_add_f32_e32 v0, v0, v7
	s_waitcnt lgkmcnt(2)
	v_add_f32_e32 v0, v0, v8
	v_add_f32_e32 v0, v0, v9
	s_waitcnt lgkmcnt(1)
	v_add_f32_e32 v0, v0, v10
	v_add_f32_e32 v0, v0, v11
	s_waitcnt lgkmcnt(0)
	v_add_f32_e32 v0, v0, v12
	v_add_f32_e32 v0, v0, v13
	v_lshlrev_b32_e32 v6, 16, v14
	v_add_f32_e32 v0, v0, v6
	v_mul_f32_e32 v6, v0, v0
	s_nop 1
	v_mov_b32_dpp v6, v6 quad_perm:[1,0,3,2] row_mask:0xf bank_mask:0xf bound_ctrl:1
	v_fmac_f32_e32 v6, v0, v0
	v_cvt_pk_bf16_f32 v0, v0, s0
	global_store_short v[2:3], v0, off
	v_add_f32_dpp v6, v6, v6 quad_perm:[2,3,0,1] row_mask:0xf bank_mask:0xf bound_ctrl:1
	s_nop 1
	v_add_f32_dpp v6, v6, v6 row_half_mirror row_mask:0xf bank_mask:0xf bound_ctrl:1
	s_nop 1
	v_add_f32_dpp v6, v6, v6 row_mirror row_mask:0xf bank_mask:0xf bound_ctrl:1
	ds_swizzle_b32 v7, v6 offset:swizzle(SWAP,16)
	s_waitcnt lgkmcnt(0)
	v_add_f32_e32 v0, v6, v7
	v_mov_b32_e32 v2, v0
	s_nop 1
	v_permlane32_swap_b32_e32 v0, v2
	s_and_saveexec_b64 s[6:7], vcc
	s_cbranch_execz .LBB0_714
	s_lshl_b64 s[4:5], s[4:5], 6
	s_add_u32 s4, s31, s4
	v_add_f32_e32 v0, v0, v2
	s_addc_u32 s5, s34, s5
	global_store_dword v1, v0, s[4:5]
	s_branch .LBB0_714

; __device__ __forceinline__ unsigned pk2(float lo, float hi) { f32x2_t v = {lo, hi}; bf16x2_t b = __builtin_convertvector(v, bf16x2_t); return __builtin_bit_cast(unsigned, b); }
; __device__ __forceinline__ float bf1(bf16 b) { return __uint_as_float((unsigned)b << 16); }
; __device__ __forceinline__ float wave_sum(float v) { v = sum16(v); v += lane_xor<16>(v); return xhalf_sum(v); }
; template <bool FIRST> __device__ __forceinline__ void skinny_resid(const bf16* __restrict__ A, const bf16* __restrict__ Bt, int K, const float* xs, bf16* XB, float* SS, int u, LAS unsigned char* lds, int tid) {
;     ...
;     for (int rr = 0; rr < 2; ++rr) { const int lr = 2 * w + rr;
;         const int ct = lane >> 4, src_lane = (lr >> 2) * 16 + (lane & 15), reg = lr & 3;
;         float s = 0.f;
; #pragma unroll
;         for (int ww = 0; ww < 8; ++ww) s += red[((ww * 4 + ct) * 64 + src_lane) * 4 + reg];
;         const int srow = 16 * rt + lr; const size_t row = (size_t)NP + srow; const int col = 64 * cu + lane;
;         const float x = (FIRST ? xs[(size_t)srow * D + col] : bf1(XB[row * D + col])) + s;
;         XB[row * D + col] = (bf16)(pk2(x, 0.f) & 0xffffu);
;         const float sq = wave_sum(x * x);
;         if (lane == 0) SS[row * 16 + cu] = sq; }
.LBB0_1314:
	s_or_b64 exec, exec, s[42:43]
	s_or_b32 s37, s41, 1
	s_add_i32 s0, s37, s40
	s_ashr_i32 s1, s0, 31
	s_lshl_b64 s[40:41], s[0:1], 11
	v_lshl_add_u64 v[0:1], v[0:1], 0, s[40:41]
	v_mov_b32_e32 v10, v242
	s_and_b32 s37, s37, 3
	s_lshl_b32 s37, s37, 2
	s_add_i32 s37, s37, 0
	v_add3_u32 v8, s37, v2, v3
	ds_read2st64_b32 v[2:3], v8 offset1:16
	ds_read2st64_b32 v[4:5], v8 offset0:32 offset1:48
	ds_read2st64_b32 v[6:7], v8 offset0:64 offset1:80
	ds_read2st64_b32 v[8:9], v8 offset0:96 offset1:112
	s_waitcnt lgkmcnt(3)
	v_add_f32_e32 v2, 0, v2
	v_add_f32_e32 v2, v2, v3
	s_waitcnt lgkmcnt(2)
	v_add_f32_e32 v2, v2, v4
	v_add_f32_e32 v2, v2, v5
	s_waitcnt lgkmcnt(1)
	v_add_f32_e32 v2, v2, v6
	v_add_f32_e32 v2, v2, v7
	s_waitcnt lgkmcnt(0)
	v_add_f32_e32 v2, v2, v8
	v_add_f32_e32 v2, v2, v9
	v_lshlrev_b32_e32 v3, 16, v10
	v_add_f32_e32 v2, v2, v3
	v_mul_f32_e32 v3, v2, v2
	s_nop 1
	v_mov_b32_dpp v3, v3 quad_perm:[1,0,3,2] row_mask:0xf bank_mask:0xf bound_ctrl:1
	v_fmac_f32_e32 v3, v2, v2
	v_cvt_pk_bf16_f32 v2, v2, s0
	global_store_short v[0:1], v2, off
	v_add_f32_dpp v3, v3, v3 quad_perm:[2,3,0,1] row_mask:0xf bank_mask:0xf bound_ctrl:1
	s_nop 1
	v_add_f32_dpp v3, v3, v3 row_half_mirror row_mask:0xf bank_mask:0xf bound_ctrl:1
	s_nop 1
	v_add_f32_dpp v3, v3, v3 row_mirror row_mask:0xf bank_mask:0xf bound_ctrl:1
	ds_swizzle_b32 v4, v3 offset:swizzle(SWAP,16)
	s_waitcnt lgkmcnt(0)
	v_add_f32_e32 v0, v3, v4
	v_mov_b32_e32 v1, v0
	s_nop 1
	v_permlane32_swap_b32_e32 v0, v1
	s_and_saveexec_b64 s[42:43], vcc
	s_cbranch_execz .LBB0_1307
	s_lshl_b64 s[0:1], s[0:1], 6
	s_add_u32 s0, s18, s0
	v_add_f32_e32 v0, v0, v1
	s_addc_u32 s1, s38, s1
	global_store_dword v19, v0, s[0:1]
	s_branch .LBB0_1307

; __device__ __forceinline__ unsigned pk2(float lo, float hi) { f32x2_t v = {lo, hi}; bf16x2_t b = __builtin_convertvector(v, bf16x2_t); return __builtin_bit_cast(unsigned, b); }
; __device__ __forceinline__ float bf1(bf16 b) { return __uint_as_float((unsigned)b << 16); }
; __device__ __forceinline__ float wave_sum(float v) { v = sum16(v); v += lane_xor<16>(v); return xhalf_sum(v); }
; template <bool FIRST> __device__ __forceinline__ void skinny_resid(const bf16* __restrict__ A, const bf16* __restrict__ Bt, int K, const float* xs, bf16* XB, float* SS, int u, LAS unsigned char* lds, int tid) {
;     ...
;     for (int rr = 0; rr < 2; ++rr) { const int lr = 2 * w + rr;
;         const int ct = lane >> 4, src_lane = (lr >> 2) * 16 + (lane & 15), reg = lr & 3;
;         float s = 0.f;
; #pragma unroll
;         for (int ww = 0; ww < 8; ++ww) s += red[((ww * 4 + ct) * 64 + src_lane) * 4 + reg];
;         const int srow = 16 * rt + lr; const size_t row = (size_t)NP + srow; const int col = 64 * cu + lane;
;         const float x = (FIRST ? xs[(size_t)srow * D + col] : bf1(XB[row * D + col])) + s;
;         XB[row * D + col] = (bf16)(pk2(x, 0.f) & 0xffffu);
;         const float sq = wave_sum(x * x);
;         if (lane == 0) SS[row * 16 + cu] = sq; }
.LBB0_2982:
	s_or_b64 exec, exec, s[8:9]
	s_or_b32 s25, s25, 1
	s_add_i32 s6, s25, s24
	s_ashr_i32 s7, s6, 31
	s_lshl_b64 s[8:9], s[6:7], 11
	v_lshl_add_u64 v[2:3], v[2:3], 0, s[8:9]
	v_mov_b32_e32 v14, v242
	s_and_b32 s8, s25, 3
	s_lshl_b32 s8, s8, 2
	s_add_i32 s8, s8, 0
	v_add3_u32 v0, s8, v0, v5
	ds_read2st64_b32 v[6:7], v0 offset1:16
	ds_read2st64_b32 v[8:9], v0 offset0:32 offset1:48
	ds_read2st64_b32 v[10:11], v0 offset0:64 offset1:80
	ds_read2st64_b32 v[12:13], v0 offset0:96 offset1:112
	s_waitcnt lgkmcnt(3)
	v_add_f32_e32 v0, 0, v6
	v_add_f32_e32 v0, v0, v7
	s_waitcnt lgkmcnt(2)
	v_add_f32_e32 v0, v0, v8
	v_add_f32_e32 v0, v0, v9
	s_waitcnt lgkmcnt(1)
	v_add_f32_e32 v0, v0, v10
	v_add_f32_e32 v0, v0, v11
	s_waitcnt lgkmcnt(0)
	v_add_f32_e32 v0, v0, v12
	v_add_f32_e32 v0, v0, v13
	v_lshlrev_b32_e32 v5, 16, v14
	v_add_f32_e32 v0, v0, v5
	v_mul_f32_e32 v5, v0, v0
	s_nop 1
	v_mov_b32_dpp v5, v5 quad_perm:[1,0,3,2] row_mask:0xf bank_mask:0xf bound_ctrl:1
	v_fmac_f32_e32 v5, v0, v0
	v_cvt_pk_bf16_f32 v0, v0, s0
	global_store_short v[2:3], v0, off
	v_add_f32_dpp v5, v5, v5 quad_perm:[2,3,0,1] row_mask:0xf bank_mask:0xf bound_ctrl:1
	s_nop 1
	v_add_f32_dpp v5, v5, v5 row_half_mirror row_mask:0xf bank_mask:0xf bound_ctrl:1
	s_nop 1
	v_add_f32_dpp v5, v5, v5 row_mirror row_mask:0xf bank_mask:0xf bound_ctrl:1
	ds_swizzle_b32 v6, v5 offset:swizzle(SWAP,16)
	s_waitcnt lgkmcnt(0)
	v_add_f32_e32 v0, v5, v6
	v_mov_b32_e32 v2, v0
	s_nop 1
	v_permlane32_swap_b32_e32 v0, v2
	s_and_saveexec_b64 s[8:9], vcc
	s_cbranch_execz .LBB0_2979
	s_lshl_b64 s[6:7], s[6:7], 6
	s_add_u32 s6, s22, s6
	v_add_f32_e32 v0, v0, v2
	s_addc_u32 s7, s23, s7
	global_store_dword v1, v0, s[6:7]
	s_branch .LBB0_2979

; __device__ __forceinline__ unsigned pk2(float lo, float hi) { f32x2_t v = {lo, hi}; bf16x2_t b = __builtin_convertvector(v, bf16x2_t); return __builtin_bit_cast(unsigned, b); }
; __device__ __forceinline__ float bf1(bf16 b) { return __uint_as_float((unsigned)b << 16); }
; __device__ __forceinline__ float wave_sum(float v) { v = sum16(v); v += lane_xor<16>(v); return xhalf_sum(v); }
; template <bool FIRST> __device__ __forceinline__ void skinny_resid(const bf16* __restrict__ A, const bf16* __restrict__ Bt, int K, const float* xs, bf16* XB, float* SS, int u, LAS unsigned char* lds, int tid) {
;     ...
;     for (int rr = 0; rr < 2; ++rr) { const int lr = 2 * w + rr;
;         const int ct = lane >> 4, src_lane = (lr >> 2) * 16 + (lane & 15), reg = lr & 3;
;         float s = 0.f;
; #pragma unroll
;         for (int ww = 0; ww < 8; ++ww) s += red[((ww * 4 + ct) * 64 + src_lane) * 4 + reg];
;         const int srow = 16 * rt + lr; const size_t row = (size_t)NP + srow; const int col = 64 * cu + lane;
;         const float x = (FIRST ? xs[(size_t)srow * D + col] : bf1(XB[row * D + col])) + s;
;         XB[row * D + col] = (bf16)(pk2(x, 0.f) & 0xffffu);
;         const float sq = wave_sum(x * x);
;         if (lane == 0) SS[row * 16 + cu] = sq; }
.LBB0_3167:
	s_or_b64 exec, exec, s[10:11]
	s_or_b32 s27, s27, 1
	s_add_i32 s0, s27, s26
	s_ashr_i32 s1, s0, 31
	s_lshl_b64 s[10:11], s[0:1], 11
	v_lshl_add_u64 v[0:1], v[0:1], 0, s[10:11]
	v_mov_b32_e32 v10, v242
	s_and_b32 s10, s27, 3
	s_lshl_b32 s10, s10, 2
	s_add_i32 s10, s10, 0
	v_add3_u32 v8, s10, v2, v3
	ds_read2st64_b32 v[2:3], v8 offset1:16
	ds_read2st64_b32 v[4:5], v8 offset0:32 offset1:48
	ds_read2st64_b32 v[6:7], v8 offset0:64 offset1:80
	ds_read2st64_b32 v[8:9], v8 offset0:96 offset1:112
	s_waitcnt lgkmcnt(3)
	v_add_f32_e32 v2, 0, v2
	v_add_f32_e32 v2, v2, v3
	s_waitcnt lgkmcnt(2)
	v_add_f32_e32 v2, v2, v4
	v_add_f32_e32 v2, v2, v5
	s_waitcnt lgkmcnt(1)
	v_add_f32_e32 v2, v2, v6
	v_add_f32_e32 v2, v2, v7
	s_waitcnt lgkmcnt(0)
	v_add_f32_e32 v2, v2, v8
	v_add_f32_e32 v2, v2, v9
	v_lshlrev_b32_e32 v3, 16, v10
	v_add_f32_e32 v2, v2, v3
	v_mul_f32_e32 v3, v2, v2
	s_nop 1
	v_mov_b32_dpp v3, v3 quad_perm:[1,0,3,2] row_mask:0xf bank_mask:0xf bound_ctrl:1
	v_fmac_f32_e32 v3, v2, v2
	v_cvt_pk_bf16_f32 v2, v2, s0
	global_store_short v[0:1], v2, off
	v_add_f32_dpp v3, v3, v3 quad_perm:[2,3,0,1] row_mask:0xf bank_mask:0xf bound_ctrl:1
	s_nop 1
	v_add_f32_dpp v3, v3, v3 row_half_mirror row_mask:0xf bank_mask:0xf bound_ctrl:1
	s_nop 1
	v_add_f32_dpp v3, v3, v3 row_mirror row_mask:0xf bank_mask:0xf bound_ctrl:1
	ds_swizzle_b32 v4, v3 offset:swizzle(SWAP,16)
	s_waitcnt lgkmcnt(0)
	v_add_f32_e32 v0, v3, v4
	v_mov_b32_e32 v1, v0
	s_nop 1
	v_permlane32_swap_b32_e32 v0, v1
	s_and_saveexec_b64 s[10:11], vcc
	s_cbranch_execz .LBB0_3160
	s_lshl_b64 s[0:1], s[0:1], 6
	s_add_u32 s0, s6, s0
	v_add_f32_e32 v0, v0, v1
	s_addc_u32 s1, s25, s1
	global_store_dword v19, v0, s[0:1]
	s_branch .LBB0_3160

.LBB0_3223:
	s_mov_b32 s20, s14
	global_load_dwordx4 v[40:43], v[2:3], off
	global_load_dwordx4 v[44:47], v[2:3], off offset:1024
	global_load_dwordx4 v[48:51], v[2:3], off offset:2048
	global_load_dwordx4 v[52:55], v[2:3], off offset:3072
	s_add_u32 s0, s48, s2
	s_addc_u32 s1, s49, s3
	global_load_dwordx4 v[60:63], v0, s[0:1]
	global_load_dwordx4 v[64:67], v0, s[0:1] offset:16
	global_load_dwordx4 v[68:71], v0, s[0:1] offset:32
	global_load_dwordx4 v[72:75], v0, s[0:1] offset:48
	v_lshl_add_u64 v[30:31], s[48:49], 0, v[4:5]
	global_load_dwordx2 v[76:77], v[30:31], off offset:-1024
	global_load_dwordx2 v[78:79], v[30:31], off offset:-512
	global_load_dwordx2 v[80:81], v[30:31], off
	global_load_dwordx2 v[82:83], v[30:31], off offset:512
	s_add_u32 s2, s2, s4
	s_addc_u32 s3, s3, s5
	v_lshl_add_u64 v[4:5], v[4:5], 0, s[6:7]
	s_add_i32 s20, s20, s86
	s_cmpk_gt_i32 s20, 0x407f
	s_cbranch_scc1 .Lmy_p13_lastA
	s_add_u32 s0, s48, s2
	s_addc_u32 s1, s49, s3
	global_load_dwordx4 v[84:87], v0, s[0:1]
	global_load_dwordx4 v[88:91], v0, s[0:1] offset:16
	global_load_dwordx4 v[92:95], v0, s[0:1] offset:32
	global_load_dwordx4 v[96:99], v0, s[0:1] offset:48
	v_lshl_add_u64 v[30:31], s[48:49], 0, v[4:5]
	global_load_dwordx2 v[100:101], v[30:31], off offset:-1024
	global_load_dwordx2 v[102:103], v[30:31], off offset:-512
	global_load_dwordx2 v[104:105], v[30:31], off
	global_load_dwordx2 v[106:107], v[30:31], off offset:512
	s_add_u32 s2, s2, s4
	s_addc_u32 s3, s3, s5
	v_lshl_add_u64 v[4:5], v[4:5], 0, s[6:7]
	s_add_i32 s20, s20, s86
	s_waitcnt vmcnt(8)
	s_add_i32 s10, s14, 0xffffc000
	s_lshl_b64 s[0:1], s[10:11], 12
	s_add_u32 s0, s15, s0
	s_addc_u32 s1, s16, s1
	s_cmpk_lt_i32 s14, 0x4000
	s_cselect_b32 s13, s18, s1
	s_cselect_b32 s12, s17, s0
	v_add_f32_e32 v108, v60, v61
	v_add_f32_e32 v109, v62, v63
	v_add_f32_e32 v110, v64, v65
	v_add_f32_e32 v111, v66, v67
	v_add_f32_e32 v112, v68, v69
	v_add_f32_e32 v113, v70, v71
	v_add_f32_e32 v114, v72, v73
	v_add_f32_e32 v115, v74, v75
	v_add_f32_e32 v108, v108, v109
	v_add_f32_e32 v110, v110, v111
	v_add_f32_e32 v112, v112, v113
	v_add_f32_e32 v114, v114, v115
	v_add_f32_e32 v108, v108, v110
	v_add_f32_e32 v108, v108, v112
	v_add_f32_e32 v9, v108, v114
	v_fmamk_f32 v9, v9, 0x3a800000, v6
	v_mul_f32_e32 v14, 0x4f800000, v9
	v_cmp_gt_f32_e32 vcc, s19, v9
	s_nop 1
	v_cndmask_b32_e32 v9, v9, v14, vcc
	v_sqrt_f32_e32 v14, v9
	s_nop 0
	v_add_u32_e32 v15, -1, v14
	v_add_u32_e32 v18, 1, v14
	v_fma_f32 v19, -v15, v14, v9
	v_fma_f32 v20, -v18, v14, v9
	v_cmp_ge_f32_e64 s[0:1], 0, v19
	s_nop 1
	v_cndmask_b32_e64 v14, v14, v15, s[0:1]
	v_cmp_lt_f32_e64 s[0:1], 0, v20
	s_nop 1
	v_cndmask_b32_e64 v14, v14, v18, s[0:1]
	v_mul_f32_e32 v15, 0x37800000, v14
	v_cndmask_b32_e32 v14, v14, v15, vcc
	v_cmp_class_f32_e32 vcc, v9, v7
	s_nop 1
	v_cndmask_b32_e32 v9, v14, v9, vcc
	v_div_scale_f32 v14, s[0:1], v9, v9, 1.0
	v_rcp_f32_e32 v18, v14
	v_div_scale_f32 v15, vcc, 1.0, v9, 1.0
	v_fma_f32 v19, -v14, v18, 1.0
	v_fmac_f32_e32 v18, v19, v18
	v_mul_f32_e32 v19, v15, v18
	v_fma_f32 v20, -v14, v19, v15
	v_fmac_f32_e32 v19, v20, v18
	v_fma_f32 v14, -v14, v19, v15
	s_nop 1
	v_div_fmas_f32 v14, v14, v18, v19
	v_div_fixup_f32 v14, v14, v9, 1.0
	v_lshlrev_b32_e32 v116, 16, v76
	v_and_b32_e32 v117, 0xffff0000, v76
	v_lshlrev_b32_e32 v118, 16, v77
	v_and_b32_e32 v119, 0xffff0000, v77
	v_mul_f32_e32 v116, v116, v14
	v_mul_f32_e32 v117, v117, v14
	v_mul_f32_e32 v118, v118, v14
	v_mul_f32_e32 v119, v119, v14
	v_mul_f32_e32 v120, v116, v40
	v_mul_f32_e32 v121, v117, v41
	v_mul_f32_e32 v122, v118, v42
	v_mul_f32_e32 v123, v119, v43
	global_store_dwordx4 v8, v[120:123], s[12:13]
	v_lshlrev_b32_e32 v116, 16, v78
	v_and_b32_e32 v117, 0xffff0000, v78
	v_lshlrev_b32_e32 v118, 16, v79
	v_and_b32_e32 v119, 0xffff0000, v79
	v_mul_f32_e32 v116, v116, v14
	v_mul_f32_e32 v117, v117, v14
	v_mul_f32_e32 v118, v118, v14
	v_mul_f32_e32 v119, v119, v14
	v_mul_f32_e32 v120, v116, v44
	v_mul_f32_e32 v121, v117, v45
	v_mul_f32_e32 v122, v118, v46
	v_mul_f32_e32 v123, v119, v47
	global_store_dwordx4 v8, v[120:123], s[12:13] offset:1024
	v_lshlrev_b32_e32 v116, 16, v80
	v_and_b32_e32 v117, 0xffff0000, v80
	v_lshlrev_b32_e32 v118, 16, v81
	v_and_b32_e32 v119, 0xffff0000, v81
	v_mul_f32_e32 v116, v116, v14
	v_mul_f32_e32 v117, v117, v14
	v_mul_f32_e32 v118, v118, v14
	v_mul_f32_e32 v119, v119, v14
	v_mul_f32_e32 v120, v116, v48
	v_mul_f32_e32 v121, v117, v49
	v_mul_f32_e32 v122, v118, v50
	v_mul_f32_e32 v123, v119, v51
	global_store_dwordx4 v8, v[120:123], s[12:13] offset:2048
	v_lshlrev_b32_e32 v116, 16, v82
	v_and_b32_e32 v117, 0xffff0000, v82
	v_lshlrev_b32_e32 v118, 16, v83
	v_and_b32_e32 v119, 0xffff0000, v83
	v_mul_f32_e32 v116, v116, v14
	v_mul_f32_e32 v117, v117, v14
	v_mul_f32_e32 v118, v118, v14
	v_mul_f32_e32 v119, v119, v14
	v_mul_f32_e32 v120, v116, v52
	v_mul_f32_e32 v121, v117, v53
	v_mul_f32_e32 v122, v118, v54
	v_mul_f32_e32 v123, v119, v55
	global_store_dwordx4 v8, v[120:123], s[12:13] offset:3072
	s_add_i32 s14, s14, s86
	s_add_u32 s17, s17, s8
	s_addc_u32 s18, s18, s9
.Lmy_p13_loop:
	s_cmpk_gt_i32 s20, 0x407f
	s_cbranch_scc1 .Lmy_p13_lastB
	s_add_u32 s0, s48, s2
	s_addc_u32 s1, s49, s3
	global_load_dwordx4 v[60:63], v0, s[0:1]
	global_load_dwordx4 v[64:67], v0, s[0:1] offset:16
	global_load_dwordx4 v[68:71], v0, s[0:1] offset:32
	global_load_dwordx4 v[72:75], v0, s[0:1] offset:48
	v_lshl_add_u64 v[30:31], s[48:49], 0, v[4:5]
	global_load_dwordx2 v[76:77], v[30:31], off offset:-1024
	global_load_dwordx2 v[78:79], v[30:31], off offset:-512
	global_load_dwordx2 v[80:81], v[30:31], off
	global_load_dwordx2 v[82:83], v[30:31], off offset:512
	s_add_u32 s2, s2, s4
	s_addc_u32 s3, s3, s5
	v_lshl_add_u64 v[4:5], v[4:5], 0, s[6:7]
	s_add_i32 s20, s20, s86
	s_waitcnt vmcnt(12)
	s_add_i32 s10, s14, 0xffffc000
	s_lshl_b64 s[0:1], s[10:11], 12
	s_add_u32 s0, s15, s0
	s_addc_u32 s1, s16, s1
	s_cmpk_lt_i32 s14, 0x4000
	s_cselect_b32 s13, s18, s1
	s_cselect_b32 s12, s17, s0
	v_add_f32_e32 v108, v84, v85
	v_add_f32_e32 v109, v86, v87
	v_add_f32_e32 v110, v88, v89
	v_add_f32_e32 v111, v90, v91
	v_add_f32_e32 v112, v92, v93
	v_add_f32_e32 v113, v94, v95
	v_add_f32_e32 v114, v96, v97
	v_add_f32_e32 v115, v98, v99
	v_add_f32_e32 v108, v108, v109
	v_add_f32_e32 v110, v110, v111
	v_add_f32_e32 v112, v112, v113
	v_add_f32_e32 v114, v114, v115
	v_add_f32_e32 v108, v108, v110
	v_add_f32_e32 v108, v108, v112
	v_add_f32_e32 v9, v108, v114
	v_fmamk_f32 v9, v9, 0x3a800000, v6
	v_mul_f32_e32 v14, 0x4f800000, v9
	v_cmp_gt_f32_e32 vcc, s19, v9
	s_nop 1
	v_cndmask_b32_e32 v9, v9, v14, vcc
	v_sqrt_f32_e32 v14, v9
	s_nop 0
	v_add_u32_e32 v15, -1, v14
	v_add_u32_e32 v18, 1, v14
	v_fma_f32 v19, -v15, v14, v9
	v_fma_f32 v20, -v18, v14, v9
	v_cmp_ge_f32_e64 s[0:1], 0, v19
	s_nop 1
	v_cndmask_b32_e64 v14, v14, v15, s[0:1]
	v_cmp_lt_f32_e64 s[0:1], 0, v20
	s_nop 1
	v_cndmask_b32_e64 v14, v14, v18, s[0:1]
	v_mul_f32_e32 v15, 0x37800000, v14
	v_cndmask_b32_e32 v14, v14, v15, vcc
	v_cmp_class_f32_e32 vcc, v9, v7
	s_nop 1
	v_cndmask_b32_e32 v9, v14, v9, vcc
	v_div_scale_f32 v14, s[0:1], v9, v9, 1.0
	v_rcp_f32_e32 v18, v14
	v_div_scale_f32 v15, vcc, 1.0, v9, 1.0
	v_fma_f32 v19, -v14, v18, 1.0
	v_fmac_f32_e32 v18, v19, v18
	v_mul_f32_e32 v19, v15, v18
	v_fma_f32 v20, -v14, v19, v15
	v_fmac_f32_e32 v19, v20, v18
	v_fma_f32 v14, -v14, v19, v15
	s_nop 1
	v_div_fmas_f32 v14, v14, v18, v19
	v_div_fixup_f32 v14, v14, v9, 1.0
	v_lshlrev_b32_e32 v116, 16, v100
	v_and_b32_e32 v117, 0xffff0000, v100
	v_lshlrev_b32_e32 v118, 16, v101
	v_and_b32_e32 v119, 0xffff0000, v101
	v_mul_f32_e32 v116, v116, v14
	v_mul_f32_e32 v117, v117, v14
	v_mul_f32_e32 v118, v118, v14
	v_mul_f32_e32 v119, v119, v14
	v_mul_f32_e32 v120, v116, v40
	v_mul_f32_e32 v121, v117, v41
	v_mul_f32_e32 v122, v118, v42
	v_mul_f32_e32 v123, v119, v43
	global_store_dwordx4 v8, v[120:123], s[12:13]
	v_lshlrev_b32_e32 v116, 16, v102
	v_and_b32_e32 v117, 0xffff0000, v102
	v_lshlrev_b32_e32 v118, 16, v103
	v_and_b32_e32 v119, 0xffff0000, v103
	v_mul_f32_e32 v116, v116, v14
	v_mul_f32_e32 v117, v117, v14
	v_mul_f32_e32 v118, v118, v14
	v_mul_f32_e32 v119, v119, v14
	v_mul_f32_e32 v120, v116, v44
	v_mul_f32_e32 v121, v117, v45
	v_mul_f32_e32 v122, v118, v46
	v_mul_f32_e32 v123, v119, v47
	global_store_dwordx4 v8, v[120:123], s[12:13] offset:1024
	v_lshlrev_b32_e32 v116, 16, v104
	v_and_b32_e32 v117, 0xffff0000, v104
	v_lshlrev_b32_e32 v118, 16, v105
	v_and_b32_e32 v119, 0xffff0000, v105
	v_mul_f32_e32 v116, v116, v14
	v_mul_f32_e32 v117, v117, v14
	v_mul_f32_e32 v118, v118, v14
	v_mul_f32_e32 v119, v119, v14
	v_mul_f32_e32 v120, v116, v48
	v_mul_f32_e32 v121, v117, v49
	v_mul_f32_e32 v122, v118, v50
	v_mul_f32_e32 v123, v119, v51
	global_store_dwordx4 v8, v[120:123], s[12:13] offset:2048
	v_lshlrev_b32_e32 v116, 16, v106
	v_and_b32_e32 v117, 0xffff0000, v106
	v_lshlrev_b32_e32 v118, 16, v107
	v_and_b32_e32 v119, 0xffff0000, v107
	v_mul_f32_e32 v116, v116, v14
	v_mul_f32_e32 v117, v117, v14
	v_mul_f32_e32 v118, v118, v14
	v_mul_f32_e32 v119, v119, v14
	v_mul_f32_e32 v120, v116, v52
	v_mul_f32_e32 v121, v117, v53
	v_mul_f32_e32 v122, v118, v54
	v_mul_f32_e32 v123, v119, v55
	global_store_dwordx4 v8, v[120:123], s[12:13] offset:3072
	s_add_i32 s14, s14, s86
	s_add_u32 s17, s17, s8
	s_addc_u32 s18, s18, s9
	s_cmpk_gt_i32 s20, 0x407f
	s_cbranch_scc1 .Lmy_p13_lastA
	s_add_u32 s0, s48, s2
	s_addc_u32 s1, s49, s3
	global_load_dwordx4 v[84:87], v0, s[0:1]
	global_load_dwordx4 v[88:91], v0, s[0:1] offset:16
	global_load_dwordx4 v[92:95], v0, s[0:1] offset:32
	global_load_dwordx4 v[96:99], v0, s[0:1] offset:48
	v_lshl_add_u64 v[30:31], s[48:49], 0, v[4:5]
	global_load_dwordx2 v[100:101], v[30:31], off offset:-1024
	global_load_dwordx2 v[102:103], v[30:31], off offset:-512
	global_load_dwordx2 v[104:105], v[30:31], off
	global_load_dwordx2 v[106:107], v[30:31], off offset:512
	s_add_u32 s2, s2, s4
	s_addc_u32 s3, s3, s5
	v_lshl_add_u64 v[4:5], v[4:5], 0, s[6:7]
	s_add_i32 s20, s20, s86
	s_waitcnt vmcnt(12)
	s_add_i32 s10, s14, 0xffffc000
	s_lshl_b64 s[0:1], s[10:11], 12
	s_add_u32 s0, s15, s0
	s_addc_u32 s1, s16, s1
	s_cmpk_lt_i32 s14, 0x4000
	s_cselect_b32 s13, s18, s1
	s_cselect_b32 s12, s17, s0
	v_add_f32_e32 v108, v60, v61
	v_add_f32_e32 v109, v62, v63
	v_add_f32_e32 v110, v64, v65
	v_add_f32_e32 v111, v66, v67
	v_add_f32_e32 v112, v68, v69
	v_add_f32_e32 v113, v70, v71
	v_add_f32_e32 v114, v72, v73
	v_add_f32_e32 v115, v74, v75
	v_add_f32_e32 v108, v108, v109
	v_add_f32_e32 v110, v110, v111
	v_add_f32_e32 v112, v112, v113
	v_add_f32_e32 v114, v114, v115
	v_add_f32_e32 v108, v108, v110
	v_add_f32_e32 v108, v108, v112
	v_add_f32_e32 v9, v108, v114
	v_fmamk_f32 v9, v9, 0x3a800000, v6
	v_mul_f32_e32 v14, 0x4f800000, v9
	v_cmp_gt_f32_e32 vcc, s19, v9
	s_nop 1
	v_cndmask_b32_e32 v9, v9, v14, vcc
	v_sqrt_f32_e32 v14, v9
	s_nop 0
	v_add_u32_e32 v15, -1, v14
	v_add_u32_e32 v18, 1, v14
	v_fma_f32 v19, -v15, v14, v9
	v_fma_f32 v20, -v18, v14, v9
	v_cmp_ge_f32_e64 s[0:1], 0, v19
	s_nop 1
	v_cndmask_b32_e64 v14, v14, v15, s[0:1]
	v_cmp_lt_f32_e64 s[0:1], 0, v20
	s_nop 1
	v_cndmask_b32_e64 v14, v14, v18, s[0:1]
	v_mul_f32_e32 v15, 0x37800000, v14
	v_cndmask_b32_e32 v14, v14, v15, vcc
	v_cmp_class_f32_e32 vcc, v9, v7
	s_nop 1
	v_cndmask_b32_e32 v9, v14, v9, vcc
	v_div_scale_f32 v14, s[0:1], v9, v9, 1.0
	v_rcp_f32_e32 v18, v14
	v_div_scale_f32 v15, vcc, 1.0, v9, 1.0
	v_fma_f32 v19, -v14, v18, 1.0
	v_fmac_f32_e32 v18, v19, v18
	v_mul_f32_e32 v19, v15, v18
	v_fma_f32 v20, -v14, v19, v15
	v_fmac_f32_e32 v19, v20, v18
	v_fma_f32 v14, -v14, v19, v15
	s_nop 1
	v_div_fmas_f32 v14, v14, v18, v19
	v_div_fixup_f32 v14, v14, v9, 1.0
	v_lshlrev_b32_e32 v116, 16, v76
	v_and_b32_e32 v117, 0xffff0000, v76
	v_lshlrev_b32_e32 v118, 16, v77
	v_and_b32_e32 v119, 0xffff0000, v77
	v_mul_f32_e32 v116, v116, v14
	v_mul_f32_e32 v117, v117, v14
	v_mul_f32_e32 v118, v118, v14
	v_mul_f32_e32 v119, v119, v14
	v_mul_f32_e32 v120, v116, v40
	v_mul_f32_e32 v121, v117, v41
	v_mul_f32_e32 v122, v118, v42
	v_mul_f32_e32 v123, v119, v43
	global_store_dwordx4 v8, v[120:123], s[12:13]
	v_lshlrev_b32_e32 v116, 16, v78
	v_and_b32_e32 v117, 0xffff0000, v78
	v_lshlrev_b32_e32 v118, 16, v79
	v_and_b32_e32 v119, 0xffff0000, v79
	v_mul_f32_e32 v116, v116, v14
	v_mul_f32_e32 v117, v117, v14
	v_mul_f32_e32 v118, v118, v14
	v_mul_f32_e32 v119, v119, v14
	v_mul_f32_e32 v120, v116, v44
	v_mul_f32_e32 v121, v117, v45
	v_mul_f32_e32 v122, v118, v46
	v_mul_f32_e32 v123, v119, v47
	global_store_dwordx4 v8, v[120:123], s[12:13] offset:1024
	v_lshlrev_b32_e32 v116, 16, v80
	v_and_b32_e32 v117, 0xffff0000, v80
	v_lshlrev_b32_e32 v118, 16, v81
	v_and_b32_e32 v119, 0xffff0000, v81
	v_mul_f32_e32 v116, v116, v14
	v_mul_f32_e32 v117, v117, v14
	v_mul_f32_e32 v118, v118, v14
	v_mul_f32_e32 v119, v119, v14
	v_mul_f32_e32 v120, v116, v48
	v_mul_f32_e32 v121, v117, v49
	v_mul_f32_e32 v122, v118, v50
	v_mul_f32_e32 v123, v119, v51
	global_store_dwordx4 v8, v[120:123], s[12:13] offset:2048
	v_lshlrev_b32_e32 v116, 16, v82
	v_and_b32_e32 v117, 0xffff0000, v82
	v_lshlrev_b32_e32 v118, 16, v83
	v_and_b32_e32 v119, 0xffff0000, v83
	v_mul_f32_e32 v116, v116, v14
	v_mul_f32_e32 v117, v117, v14
	v_mul_f32_e32 v118, v118, v14
	v_mul_f32_e32 v119, v119, v14
	v_mul_f32_e32 v120, v116, v52
	v_mul_f32_e32 v121, v117, v53
	v_mul_f32_e32 v122, v118, v54
	v_mul_f32_e32 v123, v119, v55
	global_store_dwordx4 v8, v[120:123], s[12:13] offset:3072
	s_add_i32 s14, s14, s86
	s_add_u32 s17, s17, s8
	s_addc_u32 s18, s18, s9
	s_branch .Lmy_p13_loop
